# code placement pin: v054 with the ten K-loop heads aligned to 128 bytes, padding skipped by a branch
# baseline (speedup 1.0000x reference)
.LBB0_322:
	s_add_u32 s13, s26, 0x100
	s_addc_u32 s15, s27, 0
	s_add_u32 s24, s24, 0x40080
	v_mov_b32_e32 v2, 0
	s_addc_u32 s25, s25, 0
	s_mov_b32 s21, -2
	v_mov_b32_e32 v3, v2
	v_mov_b32_e32 v4, v2
	v_mov_b32_e32 v5, v2
	v_mov_b32_e32 v10, v2
	v_mov_b32_e32 v11, v2
	v_mov_b32_e32 v12, v2
	v_mov_b32_e32 v13, v2
	v_mov_b32_e32 v18, v2
	v_mov_b32_e32 v19, v2
	v_mov_b32_e32 v20, v2
	v_mov_b32_e32 v21, v2
	v_mov_b32_e32 v26, v2
	v_mov_b32_e32 v27, v2
	v_mov_b32_e32 v28, v2
	v_mov_b32_e32 v29, v2
	v_mov_b32_e32 v34, v2
	v_mov_b32_e32 v35, v2
	v_mov_b32_e32 v36, v2
	v_mov_b32_e32 v37, v2
	v_mov_b32_e32 v42, v2
	v_mov_b32_e32 v43, v2
	v_mov_b32_e32 v44, v2
	v_mov_b32_e32 v45, v2
	v_mov_b32_e32 v50, v2
	v_mov_b32_e32 v51, v2
	v_mov_b32_e32 v52, v2
	v_mov_b32_e32 v53, v2
	v_mov_b32_e32 v58, v2
	v_mov_b32_e32 v59, v2
	v_mov_b32_e32 v60, v2
	v_mov_b32_e32 v61, v2
	v_mov_b32_e32 v6, v2
	v_mov_b32_e32 v7, v2
	v_mov_b32_e32 v8, v2
	v_mov_b32_e32 v9, v2
	v_mov_b32_e32 v14, v2
	v_mov_b32_e32 v15, v2
	v_mov_b32_e32 v16, v2
	v_mov_b32_e32 v17, v2
	v_mov_b32_e32 v22, v2
	v_mov_b32_e32 v23, v2
	v_mov_b32_e32 v24, v2
	v_mov_b32_e32 v25, v2
	v_mov_b32_e32 v30, v2
	v_mov_b32_e32 v31, v2
	v_mov_b32_e32 v32, v2
	v_mov_b32_e32 v33, v2
	v_mov_b32_e32 v38, v2
	v_mov_b32_e32 v39, v2
	v_mov_b32_e32 v40, v2
	v_mov_b32_e32 v41, v2
	v_mov_b32_e32 v46, v2
	v_mov_b32_e32 v47, v2
	v_mov_b32_e32 v48, v2
	v_mov_b32_e32 v49, v2
	v_mov_b32_e32 v54, v2
	v_mov_b32_e32 v55, v2
	v_mov_b32_e32 v56, v2
	v_mov_b32_e32 v57, v2
	v_mov_b32_e32 v62, v2
	v_mov_b32_e32 v63, v2
	v_mov_b32_e32 v64, v2
	v_mov_b32_e32 v65, v2
	v_mov_b32_e32 v66, v2
	v_mov_b32_e32 v67, v2
	v_mov_b32_e32 v68, v2
	v_mov_b32_e32 v69, v2
	v_mov_b32_e32 v74, v2
	v_mov_b32_e32 v75, v2
	v_mov_b32_e32 v76, v2
	v_mov_b32_e32 v77, v2
	v_mov_b32_e32 v82, v2
	v_mov_b32_e32 v83, v2
	v_mov_b32_e32 v84, v2
	v_mov_b32_e32 v85, v2
	v_mov_b32_e32 v90, v2
	v_mov_b32_e32 v91, v2
	v_mov_b32_e32 v92, v2
	v_mov_b32_e32 v93, v2
	v_mov_b32_e32 v98, v2
	v_mov_b32_e32 v99, v2
	v_mov_b32_e32 v100, v2
	v_mov_b32_e32 v101, v2
	v_mov_b32_e32 v106, v2
	v_mov_b32_e32 v107, v2
	v_mov_b32_e32 v108, v2
	v_mov_b32_e32 v109, v2
	v_mov_b32_e32 v114, v2
	v_mov_b32_e32 v115, v2
	v_mov_b32_e32 v116, v2
	v_mov_b32_e32 v117, v2
	v_mov_b32_e32 v122, v2
	v_mov_b32_e32 v123, v2
	v_mov_b32_e32 v124, v2
	v_mov_b32_e32 v125, v2
	v_mov_b32_e32 v70, v2
	v_mov_b32_e32 v71, v2
	v_mov_b32_e32 v72, v2
	v_mov_b32_e32 v73, v2
	v_mov_b32_e32 v78, v2
	v_mov_b32_e32 v79, v2
	v_mov_b32_e32 v80, v2
	v_mov_b32_e32 v81, v2
	v_mov_b32_e32 v86, v2
	v_mov_b32_e32 v87, v2
	v_mov_b32_e32 v88, v2
	v_mov_b32_e32 v89, v2
	v_mov_b32_e32 v94, v2
	v_mov_b32_e32 v95, v2
	v_mov_b32_e32 v96, v2
	v_mov_b32_e32 v97, v2
	v_mov_b32_e32 v102, v2
	v_mov_b32_e32 v103, v2
	v_mov_b32_e32 v104, v2
	v_mov_b32_e32 v105, v2
	v_mov_b32_e32 v110, v2
	v_mov_b32_e32 v111, v2
	v_mov_b32_e32 v112, v2
	v_mov_b32_e32 v113, v2
	v_mov_b32_e32 v118, v2
	v_mov_b32_e32 v119, v2
	v_mov_b32_e32 v120, v2
	v_mov_b32_e32 v121, v2
	v_mov_b32_e32 v126, v2
	v_mov_b32_e32 v127, v2
	v_mov_b32_e32 v128, v2
	v_mov_b32_e32 v129, v2
	s_branch .LBB0_323
	.p2alignl 7, 3212836864

.LBB0_436:
	s_add_u32 s24, s24, 0xc000
	s_addc_u32 s25, s25, 0
	s_add_u32 s80, s26, 0x100
	v_mov_b32_e32 v2, 0
	s_addc_u32 s81, s27, 0
	s_mov_b32 s82, -2
	s_waitcnt lgkmcnt(0)
	v_mov_b32_e32 v3, v2
	v_mov_b32_e32 v4, v2
	v_mov_b32_e32 v5, v2
	v_mov_b32_e32 v6, v2
	v_mov_b32_e32 v7, v2
	v_mov_b32_e32 v8, v2
	v_mov_b32_e32 v9, v2
	v_mov_b32_e32 v18, v2
	v_mov_b32_e32 v19, v2
	v_mov_b32_e32 v20, v2
	v_mov_b32_e32 v21, v2
	v_mov_b32_e32 v22, v2
	v_mov_b32_e32 v23, v2
	v_mov_b32_e32 v24, v2
	v_mov_b32_e32 v25, v2
	v_mov_b32_e32 v34, v2
	v_mov_b32_e32 v35, v2
	v_mov_b32_e32 v36, v2
	v_mov_b32_e32 v37, v2
	v_mov_b32_e32 v38, v2
	v_mov_b32_e32 v39, v2
	v_mov_b32_e32 v40, v2
	v_mov_b32_e32 v41, v2
	v_mov_b32_e32 v50, v2
	v_mov_b32_e32 v51, v2
	v_mov_b32_e32 v52, v2
	v_mov_b32_e32 v53, v2
	v_mov_b32_e32 v54, v2
	v_mov_b32_e32 v55, v2
	v_mov_b32_e32 v56, v2
	v_mov_b32_e32 v57, v2
	v_mov_b32_e32 v10, v2
	v_mov_b32_e32 v11, v2
	v_mov_b32_e32 v12, v2
	v_mov_b32_e32 v13, v2
	v_mov_b32_e32 v14, v2
	v_mov_b32_e32 v15, v2
	v_mov_b32_e32 v16, v2
	v_mov_b32_e32 v17, v2
	v_mov_b32_e32 v26, v2
	v_mov_b32_e32 v27, v2
	v_mov_b32_e32 v28, v2
	v_mov_b32_e32 v29, v2
	v_mov_b32_e32 v30, v2
	v_mov_b32_e32 v31, v2
	v_mov_b32_e32 v32, v2
	v_mov_b32_e32 v33, v2
	v_mov_b32_e32 v42, v2
	v_mov_b32_e32 v43, v2
	v_mov_b32_e32 v44, v2
	v_mov_b32_e32 v45, v2
	v_mov_b32_e32 v46, v2
	v_mov_b32_e32 v47, v2
	v_mov_b32_e32 v48, v2
	v_mov_b32_e32 v49, v2
	v_mov_b32_e32 v58, v2
	v_mov_b32_e32 v59, v2
	v_mov_b32_e32 v60, v2
	v_mov_b32_e32 v61, v2
	v_mov_b32_e32 v62, v2
	v_mov_b32_e32 v63, v2
	v_mov_b32_e32 v64, v2
	v_mov_b32_e32 v65, v2
	v_mov_b32_e32 v66, v2
	v_mov_b32_e32 v67, v2
	v_mov_b32_e32 v68, v2
	v_mov_b32_e32 v69, v2
	v_mov_b32_e32 v70, v2
	v_mov_b32_e32 v71, v2
	v_mov_b32_e32 v72, v2
	v_mov_b32_e32 v73, v2
	v_mov_b32_e32 v82, v2
	v_mov_b32_e32 v83, v2
	v_mov_b32_e32 v84, v2
	v_mov_b32_e32 v85, v2
	v_mov_b32_e32 v86, v2
	v_mov_b32_e32 v87, v2
	v_mov_b32_e32 v88, v2
	v_mov_b32_e32 v89, v2
	v_mov_b32_e32 v98, v2
	v_mov_b32_e32 v99, v2
	v_mov_b32_e32 v100, v2
	v_mov_b32_e32 v101, v2
	v_mov_b32_e32 v102, v2
	v_mov_b32_e32 v103, v2
	v_mov_b32_e32 v104, v2
	v_mov_b32_e32 v105, v2
	v_mov_b32_e32 v130, v2
	v_mov_b32_e32 v131, v2
	v_mov_b32_e32 v132, v2
	v_mov_b32_e32 v133, v2
	v_mov_b32_e32 v134, v2
	v_mov_b32_e32 v135, v2
	v_mov_b32_e32 v136, v2
	v_mov_b32_e32 v137, v2
	v_mov_b32_e32 v74, v2
	v_mov_b32_e32 v75, v2
	v_mov_b32_e32 v76, v2
	v_mov_b32_e32 v77, v2
	v_mov_b32_e32 v78, v2
	v_mov_b32_e32 v79, v2
	v_mov_b32_e32 v80, v2
	v_mov_b32_e32 v81, v2
	v_mov_b32_e32 v90, v2
	v_mov_b32_e32 v91, v2
	v_mov_b32_e32 v92, v2
	v_mov_b32_e32 v93, v2
	v_mov_b32_e32 v94, v2
	v_mov_b32_e32 v95, v2
	v_mov_b32_e32 v96, v2
	v_mov_b32_e32 v97, v2
	v_mov_b32_e32 v106, v2
	v_mov_b32_e32 v107, v2
	v_mov_b32_e32 v108, v2
	v_mov_b32_e32 v109, v2
	v_mov_b32_e32 v110, v2
	v_mov_b32_e32 v111, v2
	v_mov_b32_e32 v112, v2
	v_mov_b32_e32 v113, v2
	v_mov_b32_e32 v146, v2
	v_mov_b32_e32 v147, v2
	v_mov_b32_e32 v148, v2
	v_mov_b32_e32 v149, v2
	v_mov_b32_e32 v150, v2
	v_mov_b32_e32 v151, v2
	v_mov_b32_e32 v152, v2
	v_mov_b32_e32 v153, v2
	s_branch .LBB0_437
	.p2alignl 7, 3212836864

.LBB0_642:
	s_add_u32 s21, s60, 0x100
	s_addc_u32 s57, s61, 0
	s_add_u32 s58, s58, 0x80080
	v_mov_b32_e32 v2, 0
	s_addc_u32 s59, s59, 0
	s_mov_b32 s64, -2
	s_waitcnt lgkmcnt(0)
	v_mov_b32_e32 v3, v2
	v_mov_b32_e32 v4, v2
	v_mov_b32_e32 v5, v2
	v_mov_b32_e32 v6, v2
	v_mov_b32_e32 v7, v2
	v_mov_b32_e32 v8, v2
	v_mov_b32_e32 v9, v2
	v_mov_b32_e32 v18, v2
	v_mov_b32_e32 v19, v2
	v_mov_b32_e32 v20, v2
	v_mov_b32_e32 v21, v2
	v_mov_b32_e32 v22, v2
	v_mov_b32_e32 v23, v2
	v_mov_b32_e32 v24, v2
	v_mov_b32_e32 v25, v2
	v_mov_b32_e32 v34, v2
	v_mov_b32_e32 v35, v2
	v_mov_b32_e32 v36, v2
	v_mov_b32_e32 v37, v2
	v_mov_b32_e32 v38, v2
	v_mov_b32_e32 v39, v2
	v_mov_b32_e32 v40, v2
	v_mov_b32_e32 v41, v2
	v_mov_b32_e32 v50, v2
	v_mov_b32_e32 v51, v2
	v_mov_b32_e32 v52, v2
	v_mov_b32_e32 v53, v2
	v_mov_b32_e32 v54, v2
	v_mov_b32_e32 v55, v2
	v_mov_b32_e32 v56, v2
	v_mov_b32_e32 v57, v2
	v_mov_b32_e32 v10, v2
	v_mov_b32_e32 v11, v2
	v_mov_b32_e32 v12, v2
	v_mov_b32_e32 v13, v2
	v_mov_b32_e32 v14, v2
	v_mov_b32_e32 v15, v2
	v_mov_b32_e32 v16, v2
	v_mov_b32_e32 v17, v2
	v_mov_b32_e32 v26, v2
	v_mov_b32_e32 v27, v2
	v_mov_b32_e32 v28, v2
	v_mov_b32_e32 v29, v2
	v_mov_b32_e32 v30, v2
	v_mov_b32_e32 v31, v2
	v_mov_b32_e32 v32, v2
	v_mov_b32_e32 v33, v2
	v_mov_b32_e32 v42, v2
	v_mov_b32_e32 v43, v2
	v_mov_b32_e32 v44, v2
	v_mov_b32_e32 v45, v2
	v_mov_b32_e32 v46, v2
	v_mov_b32_e32 v47, v2
	v_mov_b32_e32 v48, v2
	v_mov_b32_e32 v49, v2
	v_mov_b32_e32 v58, v2
	v_mov_b32_e32 v59, v2
	v_mov_b32_e32 v60, v2
	v_mov_b32_e32 v61, v2
	v_mov_b32_e32 v62, v2
	v_mov_b32_e32 v63, v2
	v_mov_b32_e32 v64, v2
	v_mov_b32_e32 v65, v2
	v_mov_b32_e32 v66, v2
	v_mov_b32_e32 v67, v2
	v_mov_b32_e32 v68, v2
	v_mov_b32_e32 v69, v2
	v_mov_b32_e32 v70, v2
	v_mov_b32_e32 v71, v2
	v_mov_b32_e32 v72, v2
	v_mov_b32_e32 v73, v2
	v_mov_b32_e32 v82, v2
	v_mov_b32_e32 v83, v2
	v_mov_b32_e32 v84, v2
	v_mov_b32_e32 v85, v2
	v_mov_b32_e32 v90, v2
	v_mov_b32_e32 v91, v2
	v_mov_b32_e32 v92, v2
	v_mov_b32_e32 v93, v2
	v_mov_b32_e32 v110, v2
	v_mov_b32_e32 v111, v2
	v_mov_b32_e32 v112, v2
	v_mov_b32_e32 v113, v2
	v_mov_b32_e32 v114, v2
	v_mov_b32_e32 v115, v2
	v_mov_b32_e32 v116, v2
	v_mov_b32_e32 v117, v2
	v_mov_b32_e32 v98, v2
	v_mov_b32_e32 v99, v2
	v_mov_b32_e32 v100, v2
	v_mov_b32_e32 v101, v2
	v_mov_b32_e32 v122, v2
	v_mov_b32_e32 v123, v2
	v_mov_b32_e32 v124, v2
	v_mov_b32_e32 v125, v2
	v_mov_b32_e32 v74, v2
	v_mov_b32_e32 v75, v2
	v_mov_b32_e32 v76, v2
	v_mov_b32_e32 v77, v2
	v_mov_b32_e32 v78, v2
	v_mov_b32_e32 v79, v2
	v_mov_b32_e32 v80, v2
	v_mov_b32_e32 v81, v2
	v_mov_b32_e32 v102, v2
	v_mov_b32_e32 v103, v2
	v_mov_b32_e32 v104, v2
	v_mov_b32_e32 v105, v2
	v_mov_b32_e32 v106, v2
	v_mov_b32_e32 v107, v2
	v_mov_b32_e32 v108, v2
	v_mov_b32_e32 v109, v2
	v_mov_b32_e32 v94, v2
	v_mov_b32_e32 v95, v2
	v_mov_b32_e32 v96, v2
	v_mov_b32_e32 v97, v2
	v_mov_b32_e32 v118, v2
	v_mov_b32_e32 v119, v2
	v_mov_b32_e32 v120, v2
	v_mov_b32_e32 v121, v2
	v_mov_b32_e32 v86, v2
	v_mov_b32_e32 v87, v2
	v_mov_b32_e32 v88, v2
	v_mov_b32_e32 v89, v2
	v_mov_b32_e32 v126, v2
	v_mov_b32_e32 v127, v2
	v_mov_b32_e32 v128, v2
	v_mov_b32_e32 v129, v2
	s_branch .LBB0_643
	.p2alignl 7, 3212836864

.LBB0_695:
	s_add_u32 s15, s56, 0x100
	s_addc_u32 s17, s57, 0
	s_add_u32 s26, s26, 0x40080
	v_mov_b32_e32 v2, 0
	s_addc_u32 s27, s27, 0
	s_mov_b32 s60, -2
	v_mov_b32_e32 v3, v2
	v_mov_b32_e32 v4, v2
	v_mov_b32_e32 v5, v2
	v_mov_b32_e32 v6, v2
	v_mov_b32_e32 v7, v2
	v_mov_b32_e32 v8, v2
	v_mov_b32_e32 v9, v2
	v_mov_b32_e32 v10, v2
	v_mov_b32_e32 v11, v2
	v_mov_b32_e32 v12, v2
	v_mov_b32_e32 v13, v2
	v_mov_b32_e32 v14, v2
	v_mov_b32_e32 v15, v2
	v_mov_b32_e32 v16, v2
	v_mov_b32_e32 v17, v2
	v_mov_b32_e32 v18, v2
	v_mov_b32_e32 v19, v2
	v_mov_b32_e32 v20, v2
	v_mov_b32_e32 v21, v2
	v_mov_b32_e32 v22, v2
	v_mov_b32_e32 v23, v2
	v_mov_b32_e32 v24, v2
	v_mov_b32_e32 v25, v2
	v_mov_b32_e32 v26, v2
	v_mov_b32_e32 v27, v2
	v_mov_b32_e32 v28, v2
	v_mov_b32_e32 v29, v2
	v_mov_b32_e32 v30, v2
	v_mov_b32_e32 v31, v2
	v_mov_b32_e32 v32, v2
	v_mov_b32_e32 v33, v2
	v_mov_b32_e32 v66, v2
	v_mov_b32_e32 v67, v2
	v_mov_b32_e32 v68, v2
	v_mov_b32_e32 v69, v2
	v_mov_b32_e32 v70, v2
	v_mov_b32_e32 v71, v2
	v_mov_b32_e32 v72, v2
	v_mov_b32_e32 v73, v2
	v_mov_b32_e32 v74, v2
	v_mov_b32_e32 v75, v2
	v_mov_b32_e32 v76, v2
	v_mov_b32_e32 v77, v2
	v_mov_b32_e32 v78, v2
	v_mov_b32_e32 v79, v2
	v_mov_b32_e32 v80, v2
	v_mov_b32_e32 v81, v2
	v_mov_b32_e32 v82, v2
	v_mov_b32_e32 v83, v2
	v_mov_b32_e32 v84, v2
	v_mov_b32_e32 v85, v2
	v_mov_b32_e32 v86, v2
	v_mov_b32_e32 v87, v2
	v_mov_b32_e32 v88, v2
	v_mov_b32_e32 v89, v2
	v_mov_b32_e32 v90, v2
	v_mov_b32_e32 v91, v2
	v_mov_b32_e32 v92, v2
	v_mov_b32_e32 v93, v2
	v_mov_b32_e32 v94, v2
	v_mov_b32_e32 v95, v2
	v_mov_b32_e32 v96, v2
	v_mov_b32_e32 v97, v2
	v_mov_b32_e32 v34, v2
	v_mov_b32_e32 v35, v2
	v_mov_b32_e32 v36, v2
	v_mov_b32_e32 v37, v2
	v_mov_b32_e32 v38, v2
	v_mov_b32_e32 v39, v2
	v_mov_b32_e32 v40, v2
	v_mov_b32_e32 v41, v2
	v_mov_b32_e32 v42, v2
	v_mov_b32_e32 v43, v2
	v_mov_b32_e32 v44, v2
	v_mov_b32_e32 v45, v2
	v_mov_b32_e32 v46, v2
	v_mov_b32_e32 v47, v2
	v_mov_b32_e32 v48, v2
	v_mov_b32_e32 v49, v2
	v_mov_b32_e32 v50, v2
	v_mov_b32_e32 v51, v2
	v_mov_b32_e32 v52, v2
	v_mov_b32_e32 v53, v2
	v_mov_b32_e32 v54, v2
	v_mov_b32_e32 v55, v2
	v_mov_b32_e32 v56, v2
	v_mov_b32_e32 v57, v2
	v_mov_b32_e32 v58, v2
	v_mov_b32_e32 v59, v2
	v_mov_b32_e32 v60, v2
	v_mov_b32_e32 v61, v2
	v_mov_b32_e32 v62, v2
	v_mov_b32_e32 v63, v2
	v_mov_b32_e32 v64, v2
	v_mov_b32_e32 v65, v2
	v_mov_b32_e32 v98, v2
	v_mov_b32_e32 v99, v2
	v_mov_b32_e32 v100, v2
	v_mov_b32_e32 v101, v2
	v_mov_b32_e32 v102, v2
	v_mov_b32_e32 v103, v2
	v_mov_b32_e32 v104, v2
	v_mov_b32_e32 v105, v2
	v_mov_b32_e32 v106, v2
	v_mov_b32_e32 v107, v2
	v_mov_b32_e32 v108, v2
	v_mov_b32_e32 v109, v2
	v_mov_b32_e32 v110, v2
	v_mov_b32_e32 v111, v2
	v_mov_b32_e32 v112, v2
	v_mov_b32_e32 v113, v2
	v_mov_b32_e32 v114, v2
	v_mov_b32_e32 v115, v2
	v_mov_b32_e32 v116, v2
	v_mov_b32_e32 v117, v2
	v_mov_b32_e32 v118, v2
	v_mov_b32_e32 v119, v2
	v_mov_b32_e32 v120, v2
	v_mov_b32_e32 v121, v2
	v_mov_b32_e32 v122, v2
	v_mov_b32_e32 v123, v2
	v_mov_b32_e32 v124, v2
	v_mov_b32_e32 v125, v2
	v_mov_b32_e32 v126, v2
	v_mov_b32_e32 v127, v2
	v_mov_b32_e32 v128, v2
	v_mov_b32_e32 v129, v2
	s_branch .LBB0_696
	.p2alignl 7, 3212836864

.LBB0_967:
	s_add_i32 s56, s9, -2
	s_add_u32 s74, s24, 0x100
	s_addc_u32 s75, s25, 0
	s_add_u32 s22, s22, 0x80080
	s_addc_u32 s23, s23, 0
	s_mov_b32 s24, 0
	s_branch .LBB0_968
	.p2alignl 7, 3212836864

.LBB0_1210:
	s_add_u32 s25, s58, 0x100
	s_addc_u32 s62, s59, 0
	s_add_u32 s56, s56, 0x80080
	v_mov_b32_e32 v2, 0
	s_addc_u32 s57, s57, 0
	s_mov_b32 s78, -2
	s_waitcnt lgkmcnt(0)
	v_mov_b32_e32 v3, v2
	v_mov_b32_e32 v4, v2
	v_mov_b32_e32 v5, v2
	v_mov_b32_e32 v6, v2
	v_mov_b32_e32 v7, v2
	v_mov_b32_e32 v8, v2
	v_mov_b32_e32 v9, v2
	v_mov_b32_e32 v18, v2
	v_mov_b32_e32 v19, v2
	v_mov_b32_e32 v20, v2
	v_mov_b32_e32 v21, v2
	v_mov_b32_e32 v22, v2
	v_mov_b32_e32 v23, v2
	v_mov_b32_e32 v24, v2
	v_mov_b32_e32 v25, v2
	v_mov_b32_e32 v34, v2
	v_mov_b32_e32 v35, v2
	v_mov_b32_e32 v36, v2
	v_mov_b32_e32 v37, v2
	v_mov_b32_e32 v38, v2
	v_mov_b32_e32 v39, v2
	v_mov_b32_e32 v40, v2
	v_mov_b32_e32 v41, v2
	v_mov_b32_e32 v50, v2
	v_mov_b32_e32 v51, v2
	v_mov_b32_e32 v52, v2
	v_mov_b32_e32 v53, v2
	v_mov_b32_e32 v54, v2
	v_mov_b32_e32 v55, v2
	v_mov_b32_e32 v56, v2
	v_mov_b32_e32 v57, v2
	v_mov_b32_e32 v10, v2
	v_mov_b32_e32 v11, v2
	v_mov_b32_e32 v12, v2
	v_mov_b32_e32 v13, v2
	v_mov_b32_e32 v14, v2
	v_mov_b32_e32 v15, v2
	v_mov_b32_e32 v16, v2
	v_mov_b32_e32 v17, v2
	v_mov_b32_e32 v26, v2
	v_mov_b32_e32 v27, v2
	v_mov_b32_e32 v28, v2
	v_mov_b32_e32 v29, v2
	v_mov_b32_e32 v30, v2
	v_mov_b32_e32 v31, v2
	v_mov_b32_e32 v32, v2
	v_mov_b32_e32 v33, v2
	v_mov_b32_e32 v42, v2
	v_mov_b32_e32 v43, v2
	v_mov_b32_e32 v44, v2
	v_mov_b32_e32 v45, v2
	v_mov_b32_e32 v46, v2
	v_mov_b32_e32 v47, v2
	v_mov_b32_e32 v48, v2
	v_mov_b32_e32 v49, v2
	v_mov_b32_e32 v58, v2
	v_mov_b32_e32 v59, v2
	v_mov_b32_e32 v60, v2
	v_mov_b32_e32 v61, v2
	v_mov_b32_e32 v62, v2
	v_mov_b32_e32 v63, v2
	v_mov_b32_e32 v64, v2
	v_mov_b32_e32 v65, v2
	v_mov_b32_e32 v66, v2
	v_mov_b32_e32 v67, v2
	v_mov_b32_e32 v68, v2
	v_mov_b32_e32 v69, v2
	v_mov_b32_e32 v70, v2
	v_mov_b32_e32 v71, v2
	v_mov_b32_e32 v72, v2
	v_mov_b32_e32 v73, v2
	v_mov_b32_e32 v82, v2
	v_mov_b32_e32 v83, v2
	v_mov_b32_e32 v84, v2
	v_mov_b32_e32 v85, v2
	v_mov_b32_e32 v86, v2
	v_mov_b32_e32 v87, v2
	v_mov_b32_e32 v88, v2
	v_mov_b32_e32 v89, v2
	v_mov_b32_e32 v98, v2
	v_mov_b32_e32 v99, v2
	v_mov_b32_e32 v100, v2
	v_mov_b32_e32 v101, v2
	v_mov_b32_e32 v102, v2
	v_mov_b32_e32 v103, v2
	v_mov_b32_e32 v104, v2
	v_mov_b32_e32 v105, v2
	v_mov_b32_e32 v122, v2
	v_mov_b32_e32 v123, v2
	v_mov_b32_e32 v124, v2
	v_mov_b32_e32 v125, v2
	v_mov_b32_e32 v126, v2
	v_mov_b32_e32 v127, v2
	v_mov_b32_e32 v128, v2
	v_mov_b32_e32 v129, v2
	v_mov_b32_e32 v74, v2
	v_mov_b32_e32 v75, v2
	v_mov_b32_e32 v76, v2
	v_mov_b32_e32 v77, v2
	v_mov_b32_e32 v78, v2
	v_mov_b32_e32 v79, v2
	v_mov_b32_e32 v80, v2
	v_mov_b32_e32 v81, v2
	v_mov_b32_e32 v90, v2
	v_mov_b32_e32 v91, v2
	v_mov_b32_e32 v92, v2
	v_mov_b32_e32 v93, v2
	v_mov_b32_e32 v94, v2
	v_mov_b32_e32 v95, v2
	v_mov_b32_e32 v96, v2
	v_mov_b32_e32 v97, v2
	v_mov_b32_e32 v106, v2
	v_mov_b32_e32 v107, v2
	v_mov_b32_e32 v108, v2
	v_mov_b32_e32 v109, v2
	v_mov_b32_e32 v114, v2
	v_mov_b32_e32 v115, v2
	v_mov_b32_e32 v116, v2
	v_mov_b32_e32 v117, v2
	v_mov_b32_e32 v130, v2
	v_mov_b32_e32 v131, v2
	v_mov_b32_e32 v132, v2
	v_mov_b32_e32 v133, v2
	v_mov_b32_e32 v134, v2
	v_mov_b32_e32 v135, v2
	v_mov_b32_e32 v136, v2
	v_mov_b32_e32 v137, v2
	s_branch .LBB0_1211
	.p2alignl 7, 3212836864

.LBB0_1445:
	s_add_u32 s26, s26, 0xc000
	s_addc_u32 s27, s27, 0
	s_add_u32 s82, s56, 0x100
	v_mov_b32_e32 v2, 0
	s_addc_u32 s83, s57, 0
	s_mov_b32 s84, -2
	s_waitcnt lgkmcnt(0)
	v_mov_b32_e32 v3, v2
	v_mov_b32_e32 v4, v2
	v_mov_b32_e32 v5, v2
	v_mov_b32_e32 v6, v2
	v_mov_b32_e32 v7, v2
	v_mov_b32_e32 v8, v2
	v_mov_b32_e32 v9, v2
	v_mov_b32_e32 v18, v2
	v_mov_b32_e32 v19, v2
	v_mov_b32_e32 v20, v2
	v_mov_b32_e32 v21, v2
	v_mov_b32_e32 v22, v2
	v_mov_b32_e32 v23, v2
	v_mov_b32_e32 v24, v2
	v_mov_b32_e32 v25, v2
	v_mov_b32_e32 v34, v2
	v_mov_b32_e32 v35, v2
	v_mov_b32_e32 v36, v2
	v_mov_b32_e32 v37, v2
	v_mov_b32_e32 v38, v2
	v_mov_b32_e32 v39, v2
	v_mov_b32_e32 v40, v2
	v_mov_b32_e32 v41, v2
	v_mov_b32_e32 v50, v2
	v_mov_b32_e32 v51, v2
	v_mov_b32_e32 v52, v2
	v_mov_b32_e32 v53, v2
	v_mov_b32_e32 v54, v2
	v_mov_b32_e32 v55, v2
	v_mov_b32_e32 v56, v2
	v_mov_b32_e32 v57, v2
	v_mov_b32_e32 v10, v2
	v_mov_b32_e32 v11, v2
	v_mov_b32_e32 v12, v2
	v_mov_b32_e32 v13, v2
	v_mov_b32_e32 v14, v2
	v_mov_b32_e32 v15, v2
	v_mov_b32_e32 v16, v2
	v_mov_b32_e32 v17, v2
	v_mov_b32_e32 v26, v2
	v_mov_b32_e32 v27, v2
	v_mov_b32_e32 v28, v2
	v_mov_b32_e32 v29, v2
	v_mov_b32_e32 v30, v2
	v_mov_b32_e32 v31, v2
	v_mov_b32_e32 v32, v2
	v_mov_b32_e32 v33, v2
	v_mov_b32_e32 v42, v2
	v_mov_b32_e32 v43, v2
	v_mov_b32_e32 v44, v2
	v_mov_b32_e32 v45, v2
	v_mov_b32_e32 v46, v2
	v_mov_b32_e32 v47, v2
	v_mov_b32_e32 v48, v2
	v_mov_b32_e32 v49, v2
	v_mov_b32_e32 v58, v2
	v_mov_b32_e32 v59, v2
	v_mov_b32_e32 v60, v2
	v_mov_b32_e32 v61, v2
	v_mov_b32_e32 v62, v2
	v_mov_b32_e32 v63, v2
	v_mov_b32_e32 v64, v2
	v_mov_b32_e32 v65, v2
	v_mov_b32_e32 v66, v2
	v_mov_b32_e32 v67, v2
	v_mov_b32_e32 v68, v2
	v_mov_b32_e32 v69, v2
	v_mov_b32_e32 v70, v2
	v_mov_b32_e32 v71, v2
	v_mov_b32_e32 v72, v2
	v_mov_b32_e32 v73, v2
	v_mov_b32_e32 v82, v2
	v_mov_b32_e32 v83, v2
	v_mov_b32_e32 v84, v2
	v_mov_b32_e32 v85, v2
	v_mov_b32_e32 v86, v2
	v_mov_b32_e32 v87, v2
	v_mov_b32_e32 v88, v2
	v_mov_b32_e32 v89, v2
	v_mov_b32_e32 v98, v2
	v_mov_b32_e32 v99, v2
	v_mov_b32_e32 v100, v2
	v_mov_b32_e32 v101, v2
	v_mov_b32_e32 v102, v2
	v_mov_b32_e32 v103, v2
	v_mov_b32_e32 v104, v2
	v_mov_b32_e32 v105, v2
	v_mov_b32_e32 v122, v2
	v_mov_b32_e32 v123, v2
	v_mov_b32_e32 v124, v2
	v_mov_b32_e32 v125, v2
	v_mov_b32_e32 v126, v2
	v_mov_b32_e32 v127, v2
	v_mov_b32_e32 v128, v2
	v_mov_b32_e32 v129, v2
	v_mov_b32_e32 v74, v2
	v_mov_b32_e32 v75, v2
	v_mov_b32_e32 v76, v2
	v_mov_b32_e32 v77, v2
	v_mov_b32_e32 v78, v2
	v_mov_b32_e32 v79, v2
	v_mov_b32_e32 v80, v2
	v_mov_b32_e32 v81, v2
	v_mov_b32_e32 v90, v2
	v_mov_b32_e32 v91, v2
	v_mov_b32_e32 v92, v2
	v_mov_b32_e32 v93, v2
	v_mov_b32_e32 v94, v2
	v_mov_b32_e32 v95, v2
	v_mov_b32_e32 v96, v2
	v_mov_b32_e32 v97, v2
	v_mov_b32_e32 v106, v2
	v_mov_b32_e32 v107, v2
	v_mov_b32_e32 v108, v2
	v_mov_b32_e32 v109, v2
	v_mov_b32_e32 v114, v2
	v_mov_b32_e32 v115, v2
	v_mov_b32_e32 v116, v2
	v_mov_b32_e32 v117, v2
	v_mov_b32_e32 v130, v2
	v_mov_b32_e32 v131, v2
	v_mov_b32_e32 v132, v2
	v_mov_b32_e32 v133, v2
	v_mov_b32_e32 v134, v2
	v_mov_b32_e32 v135, v2
	v_mov_b32_e32 v136, v2
	v_mov_b32_e32 v137, v2
	s_branch .LBB0_1446
	.p2alignl 7, 3212836864

.LBB0_1573:
	v_mov_b32_e32 v2, 0
	s_mov_b32 s60, 0
	s_mov_b64 s[56:57], -1
	s_mov_b64 s[58:59], 0
	v_mov_b32_e32 v3, v2
	v_mov_b32_e32 v4, v2
	v_mov_b32_e32 v5, v2
	v_mov_b32_e32 v6, v2
	v_mov_b32_e32 v7, v2
	v_mov_b32_e32 v8, v2
	v_mov_b32_e32 v9, v2
	v_mov_b32_e32 v10, v2
	v_mov_b32_e32 v11, v2
	v_mov_b32_e32 v12, v2
	v_mov_b32_e32 v13, v2
	v_mov_b32_e32 v18, v2
	v_mov_b32_e32 v19, v2
	v_mov_b32_e32 v20, v2
	v_mov_b32_e32 v21, v2
	v_mov_b32_e32 v26, v2
	v_mov_b32_e32 v27, v2
	v_mov_b32_e32 v28, v2
	v_mov_b32_e32 v29, v2
	v_mov_b32_e32 v34, v2
	v_mov_b32_e32 v35, v2
	v_mov_b32_e32 v36, v2
	v_mov_b32_e32 v37, v2
	v_mov_b32_e32 v42, v2
	v_mov_b32_e32 v43, v2
	v_mov_b32_e32 v44, v2
	v_mov_b32_e32 v45, v2
	v_mov_b32_e32 v50, v2
	v_mov_b32_e32 v51, v2
	v_mov_b32_e32 v52, v2
	v_mov_b32_e32 v53, v2
	v_mov_b32_e32 v14, v2
	v_mov_b32_e32 v15, v2
	v_mov_b32_e32 v16, v2
	v_mov_b32_e32 v17, v2
	v_mov_b32_e32 v22, v2
	v_mov_b32_e32 v23, v2
	v_mov_b32_e32 v24, v2
	v_mov_b32_e32 v25, v2
	v_mov_b32_e32 v30, v2
	v_mov_b32_e32 v31, v2
	v_mov_b32_e32 v32, v2
	v_mov_b32_e32 v33, v2
	v_mov_b32_e32 v38, v2
	v_mov_b32_e32 v39, v2
	v_mov_b32_e32 v40, v2
	v_mov_b32_e32 v41, v2
	v_mov_b32_e32 v46, v2
	v_mov_b32_e32 v47, v2
	v_mov_b32_e32 v48, v2
	v_mov_b32_e32 v49, v2
	v_mov_b32_e32 v54, v2
	v_mov_b32_e32 v55, v2
	v_mov_b32_e32 v56, v2
	v_mov_b32_e32 v57, v2
	v_mov_b32_e32 v58, v2
	v_mov_b32_e32 v59, v2
	v_mov_b32_e32 v60, v2
	v_mov_b32_e32 v61, v2
	v_mov_b32_e32 v62, v2
	v_mov_b32_e32 v63, v2
	v_mov_b32_e32 v64, v2
	v_mov_b32_e32 v65, v2
	v_mov_b32_e32 v66, v2
	v_mov_b32_e32 v67, v2
	v_mov_b32_e32 v68, v2
	v_mov_b32_e32 v69, v2
	v_mov_b32_e32 v70, v2
	v_mov_b32_e32 v71, v2
	v_mov_b32_e32 v72, v2
	v_mov_b32_e32 v73, v2
	v_mov_b32_e32 v74, v2
	v_mov_b32_e32 v75, v2
	v_mov_b32_e32 v76, v2
	v_mov_b32_e32 v77, v2
	v_mov_b32_e32 v82, v2
	v_mov_b32_e32 v83, v2
	v_mov_b32_e32 v84, v2
	v_mov_b32_e32 v85, v2
	v_mov_b32_e32 v90, v2
	v_mov_b32_e32 v91, v2
	v_mov_b32_e32 v92, v2
	v_mov_b32_e32 v93, v2
	v_mov_b32_e32 v98, v2
	v_mov_b32_e32 v99, v2
	v_mov_b32_e32 v100, v2
	v_mov_b32_e32 v101, v2
	v_mov_b32_e32 v106, v2
	v_mov_b32_e32 v107, v2
	v_mov_b32_e32 v108, v2
	v_mov_b32_e32 v109, v2
	v_mov_b32_e32 v114, v2
	v_mov_b32_e32 v115, v2
	v_mov_b32_e32 v116, v2
	v_mov_b32_e32 v117, v2
	v_mov_b32_e32 v78, v2
	v_mov_b32_e32 v79, v2
	v_mov_b32_e32 v80, v2
	v_mov_b32_e32 v81, v2
	v_mov_b32_e32 v86, v2
	v_mov_b32_e32 v87, v2
	v_mov_b32_e32 v88, v2
	v_mov_b32_e32 v89, v2
	v_mov_b32_e32 v94, v2
	v_mov_b32_e32 v95, v2
	v_mov_b32_e32 v96, v2
	v_mov_b32_e32 v97, v2
	v_mov_b32_e32 v102, v2
	v_mov_b32_e32 v103, v2
	v_mov_b32_e32 v104, v2
	v_mov_b32_e32 v105, v2
	v_mov_b32_e32 v110, v2
	v_mov_b32_e32 v111, v2
	v_mov_b32_e32 v112, v2
	v_mov_b32_e32 v113, v2
	v_mov_b32_e32 v118, v2
	v_mov_b32_e32 v119, v2
	v_mov_b32_e32 v120, v2
	v_mov_b32_e32 v121, v2
	v_mov_b32_e32 v122, v2
	v_mov_b32_e32 v123, v2
	v_mov_b32_e32 v124, v2
	v_mov_b32_e32 v125, v2
	v_mov_b32_e32 v126, v2
	v_mov_b32_e32 v127, v2
	v_mov_b32_e32 v128, v2
	v_mov_b32_e32 v129, v2
	s_branch .LBB0_1574
	.p2alignl 7, 3212836864

.LBB0_1614:
	s_add_u32 s25, s66, 0x100
	s_addc_u32 s26, s67, 0
	s_add_u32 s64, s64, 0x40080
	v_mov_b32_e32 v2, 0
	s_addc_u32 s65, s65, 0
	s_mov_b32 s27, -2
	s_waitcnt lgkmcnt(0)
	v_mov_b32_e32 v3, v2
	v_mov_b32_e32 v4, v2
	v_mov_b32_e32 v5, v2
	v_mov_b32_e32 v6, v2
	v_mov_b32_e32 v7, v2
	v_mov_b32_e32 v8, v2
	v_mov_b32_e32 v9, v2
	v_mov_b32_e32 v10, v2
	v_mov_b32_e32 v11, v2
	v_mov_b32_e32 v12, v2
	v_mov_b32_e32 v13, v2
	v_mov_b32_e32 v14, v2
	v_mov_b32_e32 v15, v2
	v_mov_b32_e32 v16, v2
	v_mov_b32_e32 v17, v2
	v_mov_b32_e32 v18, v2
	v_mov_b32_e32 v19, v2
	v_mov_b32_e32 v20, v2
	v_mov_b32_e32 v21, v2
	v_mov_b32_e32 v22, v2
	v_mov_b32_e32 v23, v2
	v_mov_b32_e32 v24, v2
	v_mov_b32_e32 v25, v2
	v_mov_b32_e32 v26, v2
	v_mov_b32_e32 v27, v2
	v_mov_b32_e32 v28, v2
	v_mov_b32_e32 v29, v2
	v_mov_b32_e32 v30, v2
	v_mov_b32_e32 v31, v2
	v_mov_b32_e32 v32, v2
	v_mov_b32_e32 v33, v2
	v_mov_b32_e32 v34, v2
	v_mov_b32_e32 v35, v2
	v_mov_b32_e32 v36, v2
	v_mov_b32_e32 v37, v2
	v_mov_b32_e32 v38, v2
	v_mov_b32_e32 v39, v2
	v_mov_b32_e32 v40, v2
	v_mov_b32_e32 v41, v2
	v_mov_b32_e32 v42, v2
	v_mov_b32_e32 v43, v2
	v_mov_b32_e32 v44, v2
	v_mov_b32_e32 v45, v2
	v_mov_b32_e32 v46, v2
	v_mov_b32_e32 v47, v2
	v_mov_b32_e32 v48, v2
	v_mov_b32_e32 v49, v2
	v_mov_b32_e32 v50, v2
	v_mov_b32_e32 v51, v2
	v_mov_b32_e32 v52, v2
	v_mov_b32_e32 v53, v2
	v_mov_b32_e32 v54, v2
	v_mov_b32_e32 v55, v2
	v_mov_b32_e32 v56, v2
	v_mov_b32_e32 v57, v2
	v_mov_b32_e32 v58, v2
	v_mov_b32_e32 v59, v2
	v_mov_b32_e32 v60, v2
	v_mov_b32_e32 v61, v2
	v_mov_b32_e32 v62, v2
	v_mov_b32_e32 v63, v2
	v_mov_b32_e32 v64, v2
	v_mov_b32_e32 v65, v2
	v_mov_b32_e32 v82, v2
	v_mov_b32_e32 v83, v2
	v_mov_b32_e32 v84, v2
	v_mov_b32_e32 v85, v2
	v_mov_b32_e32 v86, v2
	v_mov_b32_e32 v87, v2
	v_mov_b32_e32 v88, v2
	v_mov_b32_e32 v89, v2
	v_mov_b32_e32 v90, v2
	v_mov_b32_e32 v91, v2
	v_mov_b32_e32 v92, v2
	v_mov_b32_e32 v93, v2
	v_mov_b32_e32 v94, v2
	v_mov_b32_e32 v95, v2
	v_mov_b32_e32 v96, v2
	v_mov_b32_e32 v97, v2
	v_mov_b32_e32 v98, v2
	v_mov_b32_e32 v99, v2
	v_mov_b32_e32 v100, v2
	v_mov_b32_e32 v101, v2
	v_mov_b32_e32 v102, v2
	v_mov_b32_e32 v103, v2
	v_mov_b32_e32 v104, v2
	v_mov_b32_e32 v105, v2
	v_mov_b32_e32 v106, v2
	v_mov_b32_e32 v107, v2
	v_mov_b32_e32 v108, v2
	v_mov_b32_e32 v109, v2
	v_mov_b32_e32 v110, v2
	v_mov_b32_e32 v111, v2
	v_mov_b32_e32 v112, v2
	v_mov_b32_e32 v113, v2
	v_mov_b32_e32 v74, v2
	v_mov_b32_e32 v75, v2
	v_mov_b32_e32 v76, v2
	v_mov_b32_e32 v77, v2
	v_mov_b32_e32 v78, v2
	v_mov_b32_e32 v79, v2
	v_mov_b32_e32 v80, v2
	v_mov_b32_e32 v81, v2
	v_mov_b32_e32 v114, v2
	v_mov_b32_e32 v115, v2
	v_mov_b32_e32 v116, v2
	v_mov_b32_e32 v117, v2
	v_mov_b32_e32 v118, v2
	v_mov_b32_e32 v119, v2
	v_mov_b32_e32 v120, v2
	v_mov_b32_e32 v121, v2
	v_mov_b32_e32 v122, v2
	v_mov_b32_e32 v123, v2
	v_mov_b32_e32 v124, v2
	v_mov_b32_e32 v125, v2
	v_mov_b32_e32 v126, v2
	v_mov_b32_e32 v127, v2
	v_mov_b32_e32 v128, v2
	v_mov_b32_e32 v129, v2
	v_mov_b32_e32 v130, v2
	v_mov_b32_e32 v131, v2
	v_mov_b32_e32 v132, v2
	v_mov_b32_e32 v133, v2
	v_mov_b32_e32 v134, v2
	v_mov_b32_e32 v135, v2
	v_mov_b32_e32 v136, v2
	v_mov_b32_e32 v137, v2
	s_branch .LBB0_1615
	.p2alignl 7, 3212836864
